# speedup vs baseline: 1.0280x; 1.0142x over previous
; DI unsigned pk2(float lo, float hi) { const f32x2 v = {lo, hi}; return __builtin_bit_cast(unsigned, __builtin_convertvector(v, bf16x2_t)); }
; DI void mixer_tile(unsigned char* smem_, const Params& p, int layer, const bf16_t* __restrict__ proj, bf16_t* __restrict__ y, int tile_) {
;     ...
;         const int g = tid >> 6, win = 2 << g;
;         const int l31 = lane & 31, hi = lane >> 5;
;         const float* pw = p.in[6] + ((size_t)(layer * 4 + g) * 64) * 64;
;         bf16x8 wf[2][4];
; #pragma unroll
;         for (int eh = 0; eh < 2; ++eh)
; #pragma unroll
;             for (int kk = 0; kk < 4; ++kk) {
;                 const float* wp = pw + (size_t)(16 * kk + 8 * hi) * 64 + 32 * eh + l31;
;                 u32x4 w; w.x = pk2(wp[0], wp[64]); w.y = pk2(wp[128], wp[192]); w.z = pk2(wp[256], wp[320]); w.w = pk2(wp[384], wp[448]);
;                 wf[eh][kk] = __builtin_bit_cast(bf16x8, w);
;             }
.LBB0_178:
	s_or_b64 exec, exec, s[0:1]
	v_lshrrev_b32_sdwa v73, v208, v68 dst_sel:DWORD dst_unused:UNUSED_PAD src0_sel:DWORD src1_sel:BYTE_0
	v_or_b32_e32 v0, s16, v73
	v_ashrrev_i32_e32 v1, 31, v0
	v_readlane_b32 s36, v252, 2
	v_lshlrev_b64 v[0:1], 14, v[0:1]
	v_readlane_b32 s48, v252, 14
	v_readlane_b32 s49, v252, 15
	v_lshrrev_b32_e32 v69, 5, v26
	v_lshlrev_b32_e32 v2, 2, v67
	v_lshl_add_u64 v[0:1], s[48:49], 0, v[0:1]
	v_mov_b32_e32 v3, v129
	v_lshl_add_u64 v[4:5], v[0:1], 0, v[2:3]
	v_lshlrev_b32_e32 v6, 11, v69
	v_mov_b32_e32 v7, v129
	v_lshl_add_u64 v[12:13], v[4:5], 0, v[6:7]
	s_waitcnt lgkmcnt(0)
	s_barrier
	global_load_dword v0, v[12:13], off
	global_load_dword v18, v[12:13], off offset:256
	v_or_b32_e32 v14, 0x1000, v6
	v_mov_b32_e32 v15, v129
	v_lshl_add_u64 v[8:9], v[4:5], 0, v[14:15]
	v_mov_b32_e32 v11, v129
	v_cmp_lt_u32_sdwa s[0:1], v68, v209 src0_sel:BYTE_0 src1_sel:DWORD
	s_movk_i32 s2, 0x7f
	v_cmp_gt_u32_sdwa vcc, v68, s2 src0_sel:BYTE_0 src1_sel:DWORD
	v_cmp_eq_u32_e64 s[2:3], 3, v73
	v_lshlrev_b32_e64 v71, v73, 2
	s_or_b32 s20, s18, 1
	v_readlane_b32 s37, v252, 3
	v_readlane_b32 s38, v252, 4
	v_readlane_b32 s39, v252, 5
	v_readlane_b32 s40, v252, 6
	v_readlane_b32 s41, v252, 7
	v_readlane_b32 s42, v252, 8
	v_readlane_b32 s43, v252, 9
	v_readlane_b32 s44, v252, 10
	v_readlane_b32 s45, v252, 11
	v_readlane_b32 s46, v252, 12
	v_readlane_b32 s47, v252, 13
	v_readlane_b32 s50, v252, 16
	v_readlane_b32 s51, v252, 17
	global_load_dword v1, v[12:13], off offset:512
	global_load_dword v19, v[12:13], off offset:768
	global_load_dword v2, v[12:13], off offset:1024
	global_load_dword v20, v[12:13], off offset:1280
	global_load_dword v3, v[12:13], off offset:1536
	global_load_dword v21, v[12:13], off offset:1792
	global_load_dword v32, v[8:9], off
	global_load_dword v22, v[8:9], off offset:256
	global_load_dword v33, v[8:9], off offset:512
	global_load_dword v23, v[8:9], off offset:768
	global_load_dword v34, v[8:9], off offset:1024
	global_load_dword v24, v[8:9], off offset:1280
	global_load_dword v35, v[8:9], off offset:1536
	s_nop 0
	global_load_dword v25, v[8:9], off offset:1792
	v_or_b32_e32 v10, 0x2000, v6
	v_lshl_add_u64 v[8:9], v[4:5], 0, v[10:11]
	global_load_dword v36, v[8:9], off
	global_load_dword v26, v[8:9], off offset:256
	global_load_dword v37, v[8:9], off offset:512
	global_load_dword v27, v[8:9], off offset:768
	global_load_dword v38, v[8:9], off offset:1024
	global_load_dword v28, v[8:9], off offset:1280
	global_load_dword v39, v[8:9], off offset:1536
	s_nop 0
	global_load_dword v29, v[8:9], off offset:1792
	v_mov_b32_e32 v9, v129
	v_or_b32_e32 v8, 0x3000, v6
	v_lshl_add_u64 v[6:7], v[4:5], 0, v[8:9]
	global_load_dword v40, v[6:7], off
	global_load_dword v30, v[6:7], off offset:256
	global_load_dword v41, v[6:7], off offset:512
	global_load_dword v31, v[6:7], off offset:768
	global_load_dword v42, v[6:7], off offset:1024
	global_load_dword v56, v[6:7], off offset:1280
	global_load_dword v43, v[6:7], off offset:1536
	s_nop 0
	global_load_dword v57, v[6:7], off offset:1792
	s_waitcnt vmcnt(0)
	v_cvt_pk_bf16_f32 v0, v0, v18
	v_cvt_pk_bf16_f32 v1, v1, v19
	v_cvt_pk_bf16_f32 v2, v2, v20
	v_cvt_pk_bf16_f32 v3, v3, v21
	v_cvt_pk_bf16_f32 v32, v32, v22
	v_cvt_pk_bf16_f32 v33, v33, v23
	v_cvt_pk_bf16_f32 v34, v34, v24
	v_cvt_pk_bf16_f32 v35, v35, v25
	v_cvt_pk_bf16_f32 v36, v36, v26
	v_cvt_pk_bf16_f32 v37, v37, v27
	v_cvt_pk_bf16_f32 v38, v38, v28
	v_cvt_pk_bf16_f32 v39, v39, v29
	v_cvt_pk_bf16_f32 v40, v40, v30
	v_cvt_pk_bf16_f32 v41, v41, v31
	v_cvt_pk_bf16_f32 v42, v42, v56
	v_cvt_pk_bf16_f32 v43, v43, v57
	v_lshl_add_u64 v[16:17], v[4:5], 0, s[66:67]
	global_load_dword v58, v[12:13], off offset:128
	global_load_dword v18, v[12:13], off offset:384
	v_lshl_add_u64 v[10:11], v[16:17], 0, v[10:11]
	v_lshl_add_u64 v[8:9], v[16:17], 0, v[8:9]
	global_load_dword v59, v[12:13], off offset:640
	global_load_dword v19, v[12:13], off offset:896
	global_load_dword v60, v[12:13], off offset:1152
	global_load_dword v20, v[12:13], off offset:1408
	global_load_dword v61, v[12:13], off offset:1664
	s_nop 0
	global_load_dword v21, v[12:13], off offset:1920
	v_lshl_add_u64 v[12:13], v[16:17], 0, v[14:15]
	global_load_dword v44, v[12:13], off
	global_load_dword v22, v[12:13], off offset:256
	global_load_dword v45, v[12:13], off offset:512
	global_load_dword v23, v[12:13], off offset:768
	global_load_dword v46, v[12:13], off offset:1024
	global_load_dword v24, v[12:13], off offset:1280
	global_load_dword v47, v[12:13], off offset:1536
	s_nop 0
	global_load_dword v25, v[12:13], off offset:1792
	global_load_dword v48, v[10:11], off
	global_load_dword v26, v[10:11], off offset:256
	global_load_dword v49, v[10:11], off offset:512
	global_load_dword v27, v[10:11], off offset:768
	global_load_dword v50, v[10:11], off offset:1024
	global_load_dword v28, v[10:11], off offset:1280
	global_load_dword v51, v[10:11], off offset:1536
	s_nop 0
	global_load_dword v29, v[10:11], off offset:1792
	global_load_dword v52, v[8:9], off
	global_load_dword v30, v[8:9], off offset:256
	global_load_dword v53, v[8:9], off offset:512
	global_load_dword v31, v[8:9], off offset:768
	global_load_dword v54, v[8:9], off offset:1024
	global_load_dword v56, v[8:9], off offset:1280
	global_load_dword v55, v[8:9], off offset:1536
	s_nop 0
	global_load_dword v57, v[8:9], off offset:1792
	s_waitcnt vmcnt(0)
; DI unsigned pk2(float lo, float hi) { const f32x2 v = {lo, hi}; return __builtin_bit_cast(unsigned, __builtin_convertvector(v, bf16x2_t)); }
; DI void mixer_tile(unsigned char* smem_, const Params& p, int layer, const bf16_t* __restrict__ proj, bf16_t* __restrict__ y, int tile_) {
;     ...
;                 u32x4 w; w.x = pk2(wp[0], wp[64]); w.y = pk2(wp[128], wp[192]); w.z = pk2(wp[256], wp[320]); w.w = pk2(wp[384], wp[448]);
;                 wf[eh][kk] = __builtin_bit_cast(bf16x8, w);
;             }
;         float pv[47];
; #pragma unroll
;         for (int r = 0; r < 47; ++r) pv[r] = U[r * 256 + tid];
; #pragma unroll
;         for (int t = 0; t < 32; ++t) {
;             float s = 0.f;
; #pragma unroll
;             for (int j = 0; j < 16; ++j) s += (j < win) ? pv[t + 15 - j] : 0.f;
;             const int cnt = min(pos0 + t + 1, win);
;             U[t * 256 + tid] = s * __builtin_amdgcn_rcpf((float)cnt) - pv[t + 15];
;         }
	v_cvt_pk_bf16_f32 v4, v58, v18
	v_cvt_pk_bf16_f32 v5, v59, v19
	v_cvt_pk_bf16_f32 v6, v60, v20
	v_cvt_pk_bf16_f32 v7, v61, v21
	v_cvt_pk_bf16_f32 v44, v44, v22
	v_cvt_pk_bf16_f32 v45, v45, v23
	v_cvt_pk_bf16_f32 v46, v46, v24
	v_cvt_pk_bf16_f32 v47, v47, v25
	v_cvt_pk_bf16_f32 v48, v48, v26
	v_cvt_pk_bf16_f32 v49, v49, v27
	v_cvt_pk_bf16_f32 v50, v50, v28
	v_cvt_pk_bf16_f32 v51, v51, v29
	v_cvt_pk_bf16_f32 v52, v52, v30
	v_cvt_pk_bf16_f32 v53, v53, v31
	v_cvt_pk_bf16_f32 v54, v54, v56
	v_cvt_pk_bf16_f32 v55, v55, v57
	ds_read2st64_b32 v[74:75], v72 offset1:4
	ds_read2st64_b32 v[76:77], v72 offset0:8 offset1:12
	ds_read2st64_b32 v[78:79], v72 offset0:16 offset1:20
	ds_read2st64_b32 v[80:81], v72 offset0:24 offset1:28
	ds_read2st64_b32 v[82:83], v72 offset0:32 offset1:36
	ds_read2st64_b32 v[84:85], v72 offset0:40 offset1:44
	ds_read2st64_b32 v[64:65], v72 offset0:48 offset1:52
	ds_read2st64_b32 v[62:63], v72 offset0:56 offset1:60
	ds_read2st64_b32 v[60:61], v72 offset0:64 offset1:68
	ds_read2st64_b32 v[58:59], v72 offset0:72 offset1:76
	ds_read2st64_b32 v[56:57], v72 offset0:80 offset1:84
	ds_read2st64_b32 v[30:31], v72 offset0:88 offset1:92
	ds_read2st64_b32 v[28:29], v72 offset0:96 offset1:100
	ds_read2st64_b32 v[26:27], v72 offset0:104 offset1:108
	ds_read2st64_b32 v[24:25], v72 offset0:112 offset1:116
	ds_read2st64_b32 v[22:23], v72 offset0:120 offset1:124
	ds_read2st64_b32 v[20:21], v72 offset0:128 offset1:132
	ds_read2st64_b32 v[18:19], v72 offset0:136 offset1:140
	ds_read2st64_b32 v[14:15], v72 offset0:144 offset1:148
	ds_read2st64_b32 v[8:9], v72 offset0:152 offset1:156
	ds_read2st64_b32 v[16:17], v72 offset0:160 offset1:164
	ds_read2st64_b32 v[10:11], v72 offset0:168 offset1:172
	ds_read2st64_b32 v[12:13], v72 offset0:176 offset1:180
	ds_read_b32 v70, v72 offset:47104
	s_waitcnt lgkmcnt(14)
	v_add_f32_e32 v86, 0, v63
	v_add_f32_e32 v86, v62, v86
	v_cndmask_b32_e64 v87, v65, 0, s[0:1]
	v_add_f32_e32 v86, v87, v86
	v_cndmask_b32_e64 v90, v64, 0, s[0:1]
	v_add_f32_e32 v86, v90, v86
	v_cndmask_b32_e32 v90, 0, v85, vcc
	v_add_f32_e32 v86, v90, v86
	v_cndmask_b32_e32 v91, 0, v84, vcc
	v_add_f32_e32 v86, v91, v86
	v_cndmask_b32_e32 v93, 0, v83, vcc
	v_add_f32_e32 v86, v93, v86
	v_cndmask_b32_e32 v94, 0, v82, vcc
	v_add_f32_e32 v86, v94, v86
	v_cndmask_b32_e64 v73, 0, v81, s[2:3]
	v_add_f32_e32 v81, v73, v86
	v_cndmask_b32_e64 v80, 0, v80, s[2:3]
	v_add_f32_e32 v81, v80, v81
	v_cndmask_b32_e64 v79, 0, v79, s[2:3]
	v_add_f32_e32 v81, v79, v81
	v_cndmask_b32_e64 v78, 0, v78, s[2:3]
	v_add_f32_e32 v81, v78, v81
	v_cndmask_b32_e64 v77, 0, v77, s[2:3]
	v_add_f32_e32 v81, v77, v81
	v_cndmask_b32_e64 v76, 0, v76, s[2:3]
	v_add_f32_e32 v81, v76, v81
	v_cndmask_b32_e64 v75, 0, v75, s[2:3]
	v_add_f32_e32 v81, v75, v81
	v_cndmask_b32_e64 v74, 0, v74, s[2:3]
	v_add_f32_e32 v74, v74, v81
	v_min_u32_e32 v81, s20, v71
	v_cvt_f32_ubyte0_e32 v81, v81
	v_rcp_iflag_f32_e32 v81, v81
	v_cndmask_b32_e64 v86, v62, 0, s[0:1]
	v_cndmask_b32_e64 v82, 0, v82, s[2:3]
	s_or_b32 s20, s18, 2
	v_fma_f32 v74, v81, v74, -v63
	v_add_f32_e32 v81, 0, v60
	v_add_f32_e32 v81, v63, v81
	v_add_f32_e32 v81, v86, v81
	v_add_f32_e32 v81, v87, v81
	v_cndmask_b32_e32 v87, 0, v64, vcc
	v_add_f32_e32 v81, v87, v81
	v_add_f32_e32 v81, v90, v81
	v_add_f32_e32 v81, v91, v81
	v_add_f32_e32 v81, v93, v81
	v_add_f32_e32 v81, v82, v81
	v_add_f32_e32 v81, v73, v81
	v_add_f32_e32 v81, v80, v81
	v_add_f32_e32 v81, v79, v81
	v_add_f32_e32 v81, v78, v81
	v_add_f32_e32 v81, v77, v81
	v_add_f32_e32 v81, v76, v81
	v_add_f32_e32 v75, v75, v81
	v_min_u32_e32 v81, s20, v71
	v_cvt_f32_ubyte0_e32 v81, v81
	v_rcp_iflag_f32_e32 v81, v81
	v_cndmask_b32_e64 v83, 0, v83, s[2:3]
	s_or_b32 s20, s18, 3
	v_cndmask_b32_e64 v84, 0, v84, s[2:3]
	v_fma_f32 v75, v81, v75, -v60
	ds_write2st64_b32 v72, v74, v75 offset1:4
	v_add_f32_e32 v74, 0, v61
	v_add_f32_e32 v74, v60, v74
	v_cndmask_b32_e64 v75, v63, 0, s[0:1]
	v_add_f32_e32 v74, v75, v74
	v_add_f32_e32 v74, v86, v74
	v_cndmask_b32_e32 v81, 0, v65, vcc
	v_add_f32_e32 v74, v81, v74
	v_add_f32_e32 v74, v87, v74
	v_add_f32_e32 v74, v90, v74
	v_add_f32_e32 v74, v91, v74
	v_add_f32_e32 v74, v83, v74
	v_add_f32_e32 v74, v82, v74
	v_add_f32_e32 v74, v73, v74
	v_add_f32_e32 v74, v80, v74
	v_add_f32_e32 v74, v79, v74
	v_add_f32_e32 v74, v78, v74
	v_add_f32_e32 v74, v77, v74
	v_add_f32_e32 v74, v76, v74
	v_min_u32_e32 v76, s20, v71
	v_cvt_f32_ubyte0_e32 v76, v76
	v_rcp_iflag_f32_e32 v76, v76
	v_cndmask_b32_e64 v86, v60, 0, s[0:1]
	s_or_b32 s20, s18, 4
	v_cndmask_b32_e64 v85, 0, v85, s[2:3]
	v_fma_f32 v74, v76, v74, -v61
	v_add_f32_e32 v76, 0, v58
	v_add_f32_e32 v76, v61, v76
	v_add_f32_e32 v76, v86, v76
	v_add_f32_e32 v75, v75, v76
	v_cndmask_b32_e32 v76, 0, v62, vcc
	v_add_f32_e32 v75, v76, v75
	v_add_f32_e32 v75, v81, v75
	v_add_f32_e32 v75, v87, v75
	v_add_f32_e32 v75, v90, v75
	v_add_f32_e32 v75, v84, v75
	v_add_f32_e32 v75, v83, v75
	v_add_f32_e32 v75, v82, v75
	v_add_f32_e32 v75, v73, v75
	v_add_f32_e32 v75, v80, v75
	v_add_f32_e32 v75, v79, v75
	v_add_f32_e32 v75, v78, v75
	v_add_f32_e32 v75, v77, v75
	v_min_u32_e32 v77, s20, v71
	v_cvt_f32_ubyte0_e32 v77, v77
	v_rcp_iflag_f32_e32 v77, v77
	s_or_b32 s20, s18, 5
	v_cndmask_b32_e64 v64, 0, v64, s[2:3]
	v_cndmask_b32_e64 v65, 0, v65, s[2:3]
	v_fma_f32 v75, v77, v75, -v58
	ds_write2st64_b32 v72, v74, v75 offset0:8 offset1:12
	v_add_f32_e32 v74, 0, v59
	v_add_f32_e32 v74, v58, v74
	v_cndmask_b32_e64 v75, v61, 0, s[0:1]
	v_add_f32_e32 v74, v75, v74
	v_add_f32_e32 v74, v86, v74
	v_cndmask_b32_e32 v77, 0, v63, vcc
	v_add_f32_e32 v74, v77, v74
	v_add_f32_e32 v74, v76, v74
	v_add_f32_e32 v74, v81, v74
	v_add_f32_e32 v74, v87, v74
	v_add_f32_e32 v74, v85, v74
	v_add_f32_e32 v74, v84, v74
	v_add_f32_e32 v74, v83, v74
	v_add_f32_e32 v74, v82, v74
	v_add_f32_e32 v74, v73, v74
	v_add_f32_e32 v74, v80, v74
	v_add_f32_e32 v74, v79, v74
	v_add_f32_e32 v74, v78, v74
	v_min_u32_e32 v78, s20, v71
	v_cvt_f32_ubyte0_e32 v78, v78
	v_rcp_iflag_f32_e32 v78, v78
	v_cndmask_b32_e64 v86, v58, 0, s[0:1]
	s_or_b32 s20, s18, 6
	v_cndmask_b32_e64 v62, 0, v62, s[2:3]
	v_fma_f32 v74, v78, v74, -v59
	s_waitcnt lgkmcnt(14)
; DI void mixer_tile(unsigned char* smem_, const Params& p, int layer, const bf16_t* __restrict__ proj, bf16_t* __restrict__ y, int tile_) {
;     ...
;         float pv[47];
; #pragma unroll
;         for (int r = 0; r < 47; ++r) pv[r] = U[r * 256 + tid];
; #pragma unroll
;         for (int t = 0; t < 32; ++t) {
;             float s = 0.f;
; #pragma unroll
;             for (int j = 0; j < 16; ++j) s += (j < win) ? pv[t + 15 - j] : 0.f;
;             const int cnt = min(pos0 + t + 1, win);
;             U[t * 256 + tid] = s * __builtin_amdgcn_rcpf((float)cnt) - pv[t + 15];
;         }
	v_add_f32_e32 v78, 0, v56
	v_add_f32_e32 v78, v59, v78
	v_add_f32_e32 v78, v86, v78
	v_add_f32_e32 v75, v75, v78
	v_cndmask_b32_e32 v78, 0, v60, vcc
	v_add_f32_e32 v75, v78, v75
	v_add_f32_e32 v75, v77, v75
	v_add_f32_e32 v75, v76, v75
	v_add_f32_e32 v75, v81, v75
	v_add_f32_e32 v75, v64, v75
	v_add_f32_e32 v75, v85, v75
	v_add_f32_e32 v75, v84, v75
	v_add_f32_e32 v75, v83, v75
	v_add_f32_e32 v75, v82, v75
	v_add_f32_e32 v75, v73, v75
	v_add_f32_e32 v75, v80, v75
	v_add_f32_e32 v75, v79, v75
	v_min_u32_e32 v79, s20, v71
	v_cvt_f32_ubyte0_e32 v79, v79
	v_rcp_iflag_f32_e32 v79, v79
	s_or_b32 s20, s18, 7
	v_cndmask_b32_e64 v63, 0, v63, s[2:3]
	v_cndmask_b32_e64 v60, 0, v60, s[2:3]
	v_fma_f32 v75, v79, v75, -v56
	ds_write2st64_b32 v72, v74, v75 offset0:16 offset1:20
	v_add_f32_e32 v74, 0, v57
	v_add_f32_e32 v74, v56, v74
	v_cndmask_b32_e64 v75, v59, 0, s[0:1]
	v_add_f32_e32 v74, v75, v74
	v_add_f32_e32 v74, v86, v74
	v_cndmask_b32_e32 v79, 0, v61, vcc
	v_add_f32_e32 v74, v79, v74
	v_add_f32_e32 v74, v78, v74
	v_add_f32_e32 v74, v77, v74
	v_add_f32_e32 v74, v76, v74
	v_add_f32_e32 v74, v65, v74
	v_add_f32_e32 v74, v64, v74
	v_add_f32_e32 v74, v85, v74
	v_min_u32_e32 v76, s20, v71
	v_add_f32_e32 v74, v84, v74
	v_cvt_f32_ubyte0_e32 v76, v76
	v_add_f32_e32 v74, v83, v74
	v_rcp_iflag_f32_e32 v76, v76
	v_add_f32_e32 v74, v82, v74
	v_add_f32_e32 v74, v73, v74
	v_add_f32_e32 v74, v80, v74
	v_fma_f32 v74, v76, v74, -v57
	v_add_f32_e32 v76, 0, v30
	v_add_f32_e32 v76, v57, v76
	v_cndmask_b32_e64 v80, v56, 0, s[0:1]
	v_add_f32_e32 v76, v80, v76
	v_add_f32_e32 v75, v75, v76
	v_cndmask_b32_e32 v76, 0, v58, vcc
	v_add_f32_e32 v75, v76, v75
	v_add_f32_e32 v75, v79, v75
	v_add_f32_e32 v75, v78, v75
	v_add_f32_e32 v75, v77, v75
	v_add_f32_e32 v75, v62, v75
	v_add_f32_e32 v75, v65, v75
	v_add_f32_e32 v75, v64, v75
	v_add_f32_e32 v75, v85, v75
	v_add_f32_e32 v75, v84, v75
	v_add_f32_e32 v75, v83, v75
	v_add_f32_e32 v75, v82, v75
	s_or_b32 s20, s18, 8
	v_add_f32_e32 v73, v73, v75
	v_min_u32_e32 v75, s20, v71
	v_cvt_f32_ubyte0_e32 v75, v75
	v_rcp_iflag_f32_e32 v75, v75
	s_or_b32 s20, s18, 9
	v_min_u32_e32 v77, s20, v71
	v_cvt_f32_ubyte0_e32 v77, v77
	v_fma_f32 v73, v75, v73, -v30
	ds_write2st64_b32 v72, v74, v73 offset0:24 offset1:28
	v_add_f32_e32 v73, 0, v31
	v_add_f32_e32 v73, v30, v73
	v_cndmask_b32_e64 v74, v57, 0, s[0:1]
	v_add_f32_e32 v73, v74, v73
	v_add_f32_e32 v73, v80, v73
	v_cndmask_b32_e32 v75, 0, v59, vcc
	v_add_f32_e32 v73, v75, v73
	v_add_f32_e32 v73, v76, v73
	v_add_f32_e32 v73, v79, v73
	v_add_f32_e32 v73, v78, v73
	v_add_f32_e32 v73, v63, v73
	v_add_f32_e32 v73, v62, v73
	v_add_f32_e32 v73, v65, v73
	v_add_f32_e32 v73, v64, v73
	v_add_f32_e32 v73, v85, v73
	v_rcp_iflag_f32_e32 v77, v77
	v_add_f32_e32 v73, v84, v73
	v_add_f32_e32 v73, v83, v73
	v_add_f32_e32 v73, v82, v73
	v_fma_f32 v73, v77, v73, -v31
	s_waitcnt lgkmcnt(14)
	v_add_f32_e32 v77, 0, v28
	v_add_f32_e32 v77, v31, v77
	v_cndmask_b32_e64 v78, v30, 0, s[0:1]
	v_add_f32_e32 v77, v78, v77
	v_add_f32_e32 v74, v74, v77
	v_cndmask_b32_e32 v77, 0, v56, vcc
	v_add_f32_e32 v74, v77, v74
	v_add_f32_e32 v74, v75, v74
	v_add_f32_e32 v74, v76, v74
	v_add_f32_e32 v74, v79, v74
	v_add_f32_e32 v74, v60, v74
	v_add_f32_e32 v74, v63, v74
	s_or_b32 s20, s18, 10
	v_add_f32_e32 v74, v62, v74
	v_min_u32_e32 v79, s20, v71
	v_add_f32_e32 v74, v65, v74
	v_cvt_f32_ubyte0_e32 v79, v79
	v_add_f32_e32 v74, v64, v74
	v_rcp_iflag_f32_e32 v79, v79
	v_add_f32_e32 v74, v85, v74
	v_add_f32_e32 v74, v84, v74
	v_add_f32_e32 v74, v83, v74
	v_fma_f32 v74, v79, v74, -v28
	ds_write2st64_b32 v72, v73, v74 offset0:32 offset1:36
	v_add_f32_e32 v73, 0, v29
	v_add_f32_e32 v73, v28, v73
	v_cndmask_b32_e64 v74, v31, 0, s[0:1]
	v_add_f32_e32 v73, v74, v73
	v_add_f32_e32 v73, v78, v73
	v_cndmask_b32_e32 v78, 0, v57, vcc
	v_add_f32_e32 v73, v78, v73
	v_add_f32_e32 v73, v77, v73
	v_add_f32_e32 v73, v75, v73
	v_add_f32_e32 v73, v76, v73
	v_cndmask_b32_e64 v61, 0, v61, s[2:3]
	v_add_f32_e32 v73, v61, v73
	v_add_f32_e32 v73, v60, v73
	s_or_b32 s20, s18, 11
	v_add_f32_e32 v73, v63, v73
	v_min_u32_e32 v76, s20, v71
	v_add_f32_e32 v73, v62, v73
	v_cvt_f32_ubyte0_e32 v76, v76
	v_add_f32_e32 v73, v65, v73
	v_rcp_iflag_f32_e32 v76, v76
	v_add_f32_e32 v73, v64, v73
	v_add_f32_e32 v73, v85, v73
	v_add_f32_e32 v73, v84, v73
	v_fma_f32 v73, v76, v73, -v29
	v_add_f32_e32 v76, 0, v26
	v_add_f32_e32 v76, v29, v76
	v_cndmask_b32_e64 v79, v28, 0, s[0:1]
	v_add_f32_e32 v76, v79, v76
	v_add_f32_e32 v74, v74, v76
	v_cndmask_b32_e32 v76, 0, v30, vcc
	v_add_f32_e32 v74, v76, v74
	v_add_f32_e32 v74, v78, v74
	v_add_f32_e32 v74, v77, v74
	v_add_f32_e32 v74, v75, v74
	v_cndmask_b32_e64 v58, 0, v58, s[2:3]
	v_add_f32_e32 v74, v58, v74
	v_add_f32_e32 v74, v61, v74
	s_or_b32 s20, s18, 12
	v_add_f32_e32 v74, v60, v74
	v_min_u32_e32 v75, s20, v71
	v_add_f32_e32 v74, v63, v74
	v_cvt_f32_ubyte0_e32 v75, v75
	v_add_f32_e32 v74, v62, v74
	v_rcp_iflag_f32_e32 v75, v75
	v_add_f32_e32 v74, v65, v74
	v_add_f32_e32 v74, v64, v74
	v_add_f32_e32 v74, v85, v74
	v_fma_f32 v74, v75, v74, -v26
	ds_write2st64_b32 v72, v73, v74 offset0:40 offset1:44
	v_add_f32_e32 v73, 0, v27
	v_add_f32_e32 v73, v26, v73
	v_cndmask_b32_e64 v74, v29, 0, s[0:1]
	v_add_f32_e32 v73, v74, v73
	v_add_f32_e32 v73, v79, v73
	v_cndmask_b32_e32 v75, 0, v31, vcc
	v_add_f32_e32 v73, v75, v73
	v_add_f32_e32 v73, v76, v73
	v_add_f32_e32 v73, v78, v73
	v_add_f32_e32 v73, v77, v73
	v_cndmask_b32_e64 v59, 0, v59, s[2:3]
	v_add_f32_e32 v73, v59, v73
	v_add_f32_e32 v73, v58, v73
	v_add_f32_e32 v73, v61, v73
	v_add_f32_e32 v73, v60, v73
	v_add_f32_e32 v73, v63, v73
	v_add_f32_e32 v73, v62, v73
	v_add_f32_e32 v73, v65, v73
	s_or_b32 s20, s18, 13
	v_add_f32_e32 v64, v64, v73
	v_min_u32_e32 v73, s20, v71
	v_cvt_f32_ubyte0_e32 v73, v73
	v_rcp_iflag_f32_e32 v73, v73
	v_cndmask_b32_e64 v77, v26, 0, s[0:1]
	v_cndmask_b32_e64 v56, 0, v56, s[2:3]
	s_or_b32 s20, s18, 14
	v_fma_f32 v64, v73, v64, -v27
	s_waitcnt lgkmcnt(14)
; DI void mixer_tile(unsigned char* smem_, const Params& p, int layer, const bf16_t* __restrict__ proj, bf16_t* __restrict__ y, int tile_) {
;     ...
;         float pv[47];
; #pragma unroll
;         for (int r = 0; r < 47; ++r) pv[r] = U[r * 256 + tid];
; #pragma unroll
;         for (int t = 0; t < 32; ++t) {
;             float s = 0.f;
; #pragma unroll
;             for (int j = 0; j < 16; ++j) s += (j < win) ? pv[t + 15 - j] : 0.f;
;             const int cnt = min(pos0 + t + 1, win);
;             U[t * 256 + tid] = s * __builtin_amdgcn_rcpf((float)cnt) - pv[t + 15];
;         }
	v_add_f32_e32 v73, 0, v24
	v_add_f32_e32 v73, v27, v73
	v_add_f32_e32 v73, v77, v73
	v_add_f32_e32 v73, v74, v73
	v_cndmask_b32_e32 v74, 0, v28, vcc
	v_add_f32_e32 v73, v74, v73
	v_add_f32_e32 v73, v75, v73
	v_add_f32_e32 v73, v76, v73
	v_add_f32_e32 v73, v78, v73
	v_add_f32_e32 v73, v56, v73
	v_add_f32_e32 v73, v59, v73
	v_add_f32_e32 v73, v58, v73
	v_add_f32_e32 v73, v61, v73
	v_add_f32_e32 v73, v60, v73
	v_add_f32_e32 v73, v63, v73
	v_add_f32_e32 v73, v62, v73
	v_add_f32_e32 v65, v65, v73
	v_min_u32_e32 v73, s20, v71
	v_cvt_f32_ubyte0_e32 v73, v73
	v_rcp_iflag_f32_e32 v73, v73
	v_cndmask_b32_e64 v57, 0, v57, s[2:3]
	s_or_b32 s20, s18, 15
	v_cndmask_b32_e64 v30, 0, v30, s[2:3]
	v_fma_f32 v65, v73, v65, -v24
	ds_write2st64_b32 v72, v64, v65 offset0:48 offset1:52
	v_add_f32_e32 v64, 0, v25
	v_add_f32_e32 v64, v24, v64
	v_cndmask_b32_e64 v65, v27, 0, s[0:1]
	v_add_f32_e32 v64, v65, v64
	v_add_f32_e32 v64, v77, v64
	v_cndmask_b32_e32 v73, 0, v29, vcc
	v_add_f32_e32 v64, v73, v64
	v_add_f32_e32 v64, v74, v64
	v_add_f32_e32 v64, v75, v64
	v_add_f32_e32 v64, v76, v64
	v_add_f32_e32 v64, v57, v64
	v_add_f32_e32 v64, v56, v64
	v_add_f32_e32 v64, v59, v64
	v_add_f32_e32 v64, v58, v64
	v_add_f32_e32 v64, v61, v64
	v_add_f32_e32 v64, v60, v64
	v_add_f32_e32 v64, v63, v64
	v_add_f32_e32 v62, v62, v64
	v_min_u32_e32 v64, s20, v71
	v_cvt_f32_ubyte0_e32 v64, v64
	v_rcp_iflag_f32_e32 v64, v64
	v_cndmask_b32_e64 v76, v24, 0, s[0:1]
	v_cndmask_b32_e64 v31, 0, v31, s[2:3]
	v_cndmask_b32_e64 v28, 0, v28, s[2:3]
	v_fma_f32 v62, v64, v62, -v25
	v_add_f32_e32 v64, 0, v22
	v_add_f32_e32 v64, v25, v64
	v_add_f32_e32 v64, v76, v64
	v_add_f32_e32 v64, v65, v64
	v_cndmask_b32_e32 v65, 0, v26, vcc
	v_add_f32_e32 v64, v65, v64
	v_add_f32_e32 v64, v73, v64
	v_add_f32_e32 v64, v74, v64
	v_add_f32_e32 v64, v75, v64
	v_add_f32_e32 v64, v30, v64
	v_add_f32_e32 v64, v57, v64
	v_add_f32_e32 v64, v56, v64
	v_add_f32_e32 v64, v59, v64
	v_add_f32_e32 v64, v58, v64
	v_add_f32_e32 v64, v61, v64
	v_add_f32_e32 v64, v60, v64
	v_add_f32_e32 v63, v63, v64
	v_cvt_f32_ubyte0_e32 v64, v71
	v_rcp_iflag_f32_e32 v64, v64
	v_cndmask_b32_e32 v71, 0, v27, vcc
	v_cndmask_b32_e64 v29, 0, v29, s[2:3]
	v_cndmask_b32_e64 v26, 0, v26, s[2:3]
	v_fma_f32 v63, v64, v63, -v22
	ds_write2st64_b32 v72, v62, v63 offset0:56 offset1:60
	v_add_f32_e32 v62, 0, v23
	v_add_f32_e32 v62, v22, v62
	v_cndmask_b32_e64 v63, v25, 0, s[0:1]
	v_add_f32_e32 v62, v63, v62
	v_add_f32_e32 v62, v76, v62
	v_add_f32_e32 v62, v71, v62
	v_add_f32_e32 v62, v65, v62
	v_add_f32_e32 v62, v73, v62
	v_add_f32_e32 v62, v74, v62
	v_add_f32_e32 v62, v31, v62
	v_add_f32_e32 v62, v30, v62
	v_add_f32_e32 v62, v57, v62
	v_add_f32_e32 v62, v56, v62
	v_add_f32_e32 v62, v59, v62
	v_add_f32_e32 v62, v58, v62
	v_add_f32_e32 v62, v61, v62
	v_add_f32_e32 v60, v60, v62
	s_waitcnt lgkmcnt(14)
	v_add_f32_e32 v62, 0, v20
	v_add_f32_e32 v62, v23, v62
	v_cndmask_b32_e64 v74, v22, 0, s[0:1]
	v_add_f32_e32 v62, v74, v62
	v_add_f32_e32 v62, v63, v62
	v_cndmask_b32_e32 v63, 0, v24, vcc
	v_add_f32_e32 v62, v63, v62
	v_add_f32_e32 v62, v71, v62
	v_add_f32_e32 v62, v65, v62
	v_add_f32_e32 v62, v73, v62
	v_add_f32_e32 v62, v28, v62
	v_add_f32_e32 v62, v31, v62
	v_add_f32_e32 v62, v30, v62
	v_add_f32_e32 v62, v57, v62
	v_add_f32_e32 v62, v56, v62
	v_add_f32_e32 v62, v59, v62
	v_add_f32_e32 v62, v58, v62
	v_add_f32_e32 v61, v61, v62
	v_fma_f32 v60, v64, v60, -v23
	v_fma_f32 v61, v64, v61, -v20
	ds_write2st64_b32 v72, v60, v61 offset0:64 offset1:68
	v_add_f32_e32 v60, 0, v21
	v_add_f32_e32 v60, v20, v60
	v_cndmask_b32_e64 v61, v23, 0, s[0:1]
	v_add_f32_e32 v60, v61, v60
	v_add_f32_e32 v60, v74, v60
	v_cndmask_b32_e32 v62, 0, v25, vcc
	v_add_f32_e32 v60, v62, v60
	v_add_f32_e32 v60, v63, v60
	v_add_f32_e32 v60, v71, v60
	v_add_f32_e32 v60, v65, v60
	v_add_f32_e32 v60, v29, v60
	v_add_f32_e32 v60, v28, v60
	v_add_f32_e32 v60, v31, v60
	v_add_f32_e32 v60, v30, v60
	v_add_f32_e32 v60, v57, v60
	v_add_f32_e32 v60, v56, v60
	v_add_f32_e32 v60, v59, v60
	v_add_f32_e32 v58, v58, v60
	v_add_f32_e32 v60, 0, v18
	v_add_f32_e32 v60, v21, v60
	v_cndmask_b32_e64 v65, v20, 0, s[0:1]
	v_add_f32_e32 v60, v65, v60
	v_add_f32_e32 v60, v61, v60
	v_cndmask_b32_e32 v61, 0, v22, vcc
	v_add_f32_e32 v60, v61, v60
	v_add_f32_e32 v60, v62, v60
	v_add_f32_e32 v60, v63, v60
	v_add_f32_e32 v60, v71, v60
	v_add_f32_e32 v60, v26, v60
	v_add_f32_e32 v60, v29, v60
	v_add_f32_e32 v60, v28, v60
	v_add_f32_e32 v60, v31, v60
	v_add_f32_e32 v60, v30, v60
	v_add_f32_e32 v60, v57, v60
	v_add_f32_e32 v60, v56, v60
	v_add_f32_e32 v59, v59, v60
	v_fma_f32 v58, v64, v58, -v21
	v_fma_f32 v59, v64, v59, -v18
	ds_write2st64_b32 v72, v58, v59 offset0:72 offset1:76
	v_add_f32_e32 v58, 0, v19
	v_add_f32_e32 v58, v18, v58
	v_cndmask_b32_e64 v59, v21, 0, s[0:1]
	v_add_f32_e32 v58, v59, v58
	v_add_f32_e32 v58, v65, v58
	v_cndmask_b32_e32 v60, 0, v23, vcc
	v_add_f32_e32 v58, v60, v58
	v_add_f32_e32 v58, v61, v58
	v_add_f32_e32 v58, v62, v58
	v_add_f32_e32 v58, v63, v58
	v_cndmask_b32_e64 v27, 0, v27, s[2:3]
	v_add_f32_e32 v58, v27, v58
	v_add_f32_e32 v58, v26, v58
	v_add_f32_e32 v58, v29, v58
	v_add_f32_e32 v58, v28, v58
	v_add_f32_e32 v58, v31, v58
	v_add_f32_e32 v58, v30, v58
	v_add_f32_e32 v58, v57, v58
	v_add_f32_e32 v56, v56, v58
	s_waitcnt lgkmcnt(14)
; DI void mixer_tile(unsigned char* smem_, const Params& p, int layer, const bf16_t* __restrict__ proj, bf16_t* __restrict__ y, int tile_) {
;     ...
;         float pv[47];
; #pragma unroll
;         for (int r = 0; r < 47; ++r) pv[r] = U[r * 256 + tid];
; #pragma unroll
;         for (int t = 0; t < 32; ++t) {
;             float s = 0.f;
; #pragma unroll
;             for (int j = 0; j < 16; ++j) s += (j < win) ? pv[t + 15 - j] : 0.f;
;             const int cnt = min(pos0 + t + 1, win);
;             U[t * 256 + tid] = s * __builtin_amdgcn_rcpf((float)cnt) - pv[t + 15];
;         }
	v_add_f32_e32 v58, 0, v14
	v_add_f32_e32 v58, v19, v58
	v_cndmask_b32_e64 v63, v18, 0, s[0:1]
	v_add_f32_e32 v58, v63, v58
	v_add_f32_e32 v58, v59, v58
	v_cndmask_b32_e32 v59, 0, v20, vcc
	v_add_f32_e32 v58, v59, v58
	v_add_f32_e32 v58, v60, v58
	v_add_f32_e32 v58, v61, v58
	v_add_f32_e32 v58, v62, v58
	v_cndmask_b32_e64 v24, 0, v24, s[2:3]
	v_add_f32_e32 v58, v24, v58
	v_add_f32_e32 v58, v27, v58
	v_add_f32_e32 v58, v26, v58
	v_add_f32_e32 v58, v29, v58
	v_add_f32_e32 v58, v28, v58
	v_add_f32_e32 v58, v31, v58
	v_add_f32_e32 v58, v30, v58
	v_add_f32_e32 v57, v57, v58
	v_fma_f32 v56, v64, v56, -v19
	v_fma_f32 v57, v64, v57, -v14
	ds_write2st64_b32 v72, v56, v57 offset0:80 offset1:84
	v_add_f32_e32 v56, 0, v15
	v_add_f32_e32 v56, v14, v56
	v_cndmask_b32_e64 v57, v19, 0, s[0:1]
	v_add_f32_e32 v56, v57, v56
	v_add_f32_e32 v56, v63, v56
	v_cndmask_b32_e32 v58, 0, v21, vcc
	v_add_f32_e32 v56, v58, v56
	v_add_f32_e32 v56, v59, v56
	v_add_f32_e32 v56, v60, v56
	v_add_f32_e32 v56, v61, v56
	v_cndmask_b32_e64 v25, 0, v25, s[2:3]
	v_add_f32_e32 v56, v25, v56
	v_add_f32_e32 v56, v24, v56
	v_add_f32_e32 v56, v27, v56
	v_add_f32_e32 v56, v26, v56
	v_add_f32_e32 v56, v29, v56
	v_add_f32_e32 v56, v28, v56
	v_add_f32_e32 v56, v31, v56
	v_add_f32_e32 v30, v30, v56
	v_add_f32_e32 v56, 0, v8
	v_add_f32_e32 v56, v15, v56
	v_cndmask_b32_e64 v61, v14, 0, s[0:1]
	v_add_f32_e32 v56, v61, v56
	v_add_f32_e32 v56, v57, v56
	v_cndmask_b32_e32 v57, 0, v18, vcc
	v_add_f32_e32 v56, v57, v56
	v_add_f32_e32 v56, v58, v56
	v_add_f32_e32 v56, v59, v56
	v_add_f32_e32 v56, v60, v56
	v_cndmask_b32_e64 v22, 0, v22, s[2:3]
	v_add_f32_e32 v56, v22, v56
	v_add_f32_e32 v56, v25, v56
	v_add_f32_e32 v56, v24, v56
	v_add_f32_e32 v56, v27, v56
	v_add_f32_e32 v56, v26, v56
	v_add_f32_e32 v56, v29, v56
	v_add_f32_e32 v56, v28, v56
	v_add_f32_e32 v31, v31, v56
	v_fma_f32 v30, v64, v30, -v15
	v_fma_f32 v31, v64, v31, -v8
	ds_write2st64_b32 v72, v30, v31 offset0:88 offset1:92
	v_add_f32_e32 v30, 0, v9
	v_add_f32_e32 v30, v8, v30
	v_cndmask_b32_e64 v31, v15, 0, s[0:1]
	v_add_f32_e32 v30, v31, v30
	v_add_f32_e32 v30, v61, v30
	v_cndmask_b32_e32 v56, 0, v19, vcc
	v_add_f32_e32 v30, v56, v30
	v_add_f32_e32 v30, v57, v30
	v_add_f32_e32 v30, v58, v30
	v_add_f32_e32 v30, v59, v30
	v_cndmask_b32_e64 v23, 0, v23, s[2:3]
	v_add_f32_e32 v30, v23, v30
	v_add_f32_e32 v30, v22, v30
	v_add_f32_e32 v30, v25, v30
	v_add_f32_e32 v30, v24, v30
	v_add_f32_e32 v30, v27, v30
	v_add_f32_e32 v30, v26, v30
	v_add_f32_e32 v30, v29, v30
	v_add_f32_e32 v28, v28, v30
	s_waitcnt lgkmcnt(14)
	v_add_f32_e32 v30, 0, v16
	v_add_f32_e32 v30, v9, v30
	v_cndmask_b32_e64 v59, v8, 0, s[0:1]
	v_add_f32_e32 v30, v59, v30
	v_add_f32_e32 v30, v31, v30
	v_cndmask_b32_e32 v31, 0, v14, vcc
	v_add_f32_e32 v30, v31, v30
	v_add_f32_e32 v30, v56, v30
	v_add_f32_e32 v30, v57, v30
	v_add_f32_e32 v30, v58, v30
	v_cndmask_b32_e64 v20, 0, v20, s[2:3]
	v_add_f32_e32 v30, v20, v30
	v_add_f32_e32 v30, v23, v30
	v_add_f32_e32 v30, v22, v30
	v_add_f32_e32 v30, v25, v30
	v_add_f32_e32 v30, v24, v30
	v_add_f32_e32 v30, v27, v30
	v_add_f32_e32 v30, v26, v30
	v_add_f32_e32 v29, v29, v30
	v_fma_f32 v28, v64, v28, -v9
	v_fma_f32 v29, v64, v29, -v16
	ds_write2st64_b32 v72, v28, v29 offset0:96 offset1:100
	v_add_f32_e32 v28, 0, v17
	v_add_f32_e32 v28, v16, v28
	v_cndmask_b32_e64 v29, v9, 0, s[0:1]
	v_add_f32_e32 v28, v29, v28
	v_add_f32_e32 v28, v59, v28
	v_cndmask_b32_e32 v30, 0, v15, vcc
	v_add_f32_e32 v28, v30, v28
	v_add_f32_e32 v28, v31, v28
	v_add_f32_e32 v28, v56, v28
	v_add_f32_e32 v28, v57, v28
	v_cndmask_b32_e64 v21, 0, v21, s[2:3]
	v_add_f32_e32 v28, v21, v28
	v_add_f32_e32 v28, v20, v28
	v_add_f32_e32 v28, v23, v28
	v_add_f32_e32 v28, v22, v28
	v_add_f32_e32 v28, v25, v28
	v_add_f32_e32 v28, v24, v28
	v_add_f32_e32 v28, v27, v28
	v_add_f32_e32 v26, v26, v28
	v_add_f32_e32 v28, 0, v10
	v_add_f32_e32 v28, v17, v28
	v_cndmask_b32_e64 v57, v16, 0, s[0:1]
	v_add_f32_e32 v28, v57, v28
	v_add_f32_e32 v28, v29, v28
	v_cndmask_b32_e32 v29, 0, v8, vcc
	v_add_f32_e32 v28, v29, v28
	v_add_f32_e32 v28, v30, v28
	v_add_f32_e32 v28, v31, v28
	v_add_f32_e32 v28, v56, v28
	v_cndmask_b32_e64 v18, 0, v18, s[2:3]
	v_add_f32_e32 v28, v18, v28
	v_add_f32_e32 v28, v21, v28
	v_add_f32_e32 v28, v20, v28
	v_add_f32_e32 v28, v23, v28
	v_add_f32_e32 v28, v22, v28
	v_add_f32_e32 v28, v25, v28
	v_add_f32_e32 v28, v24, v28
	v_add_f32_e32 v27, v27, v28
	v_fma_f32 v26, v64, v26, -v17
	v_fma_f32 v27, v64, v27, -v10
	ds_write2st64_b32 v72, v26, v27 offset0:104 offset1:108
	v_add_f32_e32 v26, 0, v11
	v_add_f32_e32 v26, v10, v26
	v_cndmask_b32_e64 v27, v17, 0, s[0:1]
	v_add_f32_e32 v26, v27, v26
	v_add_f32_e32 v26, v57, v26
	v_cndmask_b32_e32 v9, 0, v9, vcc
	v_add_f32_e32 v26, v9, v26
	v_add_f32_e32 v26, v29, v26
	v_add_f32_e32 v26, v30, v26
	v_add_f32_e32 v26, v31, v26
	v_cndmask_b32_e64 v19, 0, v19, s[2:3]
	v_add_f32_e32 v26, v19, v26
	v_add_f32_e32 v26, v18, v26
	v_add_f32_e32 v26, v21, v26
	v_add_f32_e32 v26, v20, v26
	v_add_f32_e32 v26, v23, v26
	v_add_f32_e32 v26, v22, v26
	v_add_f32_e32 v26, v25, v26
	v_add_f32_e32 v24, v24, v26
	s_waitcnt lgkmcnt(14)
; #define MFMA32(a, b, c) __builtin_amdgcn_mfma_f32_32x32x16_bf16((a), (b), (c), 0, 0, 0)
; DI unsigned pk2(float lo, float hi) { const f32x2 v = {lo, hi}; return __builtin_bit_cast(unsigned, __builtin_convertvector(v, bf16x2_t)); }
; DI void mixer_tile(unsigned char* smem_, const Params& p, int layer, const bf16_t* __restrict__ proj, bf16_t* __restrict__ y, int tile_) {
;     ...
;             U[t * 256 + tid] = s * __builtin_amdgcn_rcpf((float)cnt) - pv[t + 15];
;         }
;         __syncthreads();
;         f32x16 acc[2];
; #pragma unroll
;         for (int i = 0; i < 16; ++i) { acc[0][i] = 0.f; acc[1][i] = 0.f; }
; #pragma unroll
;         for (int kk = 0; kk < 4; ++kk) {
;             const float* pp = U + l31 * 256 + g * 64 + 16 * kk + 8 * hi;
;             const f32x4 pa = *(const f32x4*)(pp), pb = *(const f32x4*)(pp + 4);
;             u32x4 pk; pk.x = pk2(pa.x, pa.y); pk.y = pk2(pa.z, pa.w); pk.z = pk2(pb.x, pb.y); pk.w = pk2(pb.z, pb.w);
;             const bf16x8 pf = __builtin_bit_cast(bf16x8, pk);
;             acc[0] = MFMA32(wf[0][kk], pf, acc[0]);
;             acc[1] = MFMA32(wf[1][kk], pf, acc[1]);
;         }
;         const float* scp = p.in[7] + layer * 256 + g * 64;
;         bf16_t* yr = y + (size_t)(tok0 + l31) * PA + 256 + g * 64 + 4 * hi;
; #pragma unroll
;         for (int eh = 0; eh < 2; ++eh)
; #pragma unroll
;             for (int gq = 0; gq < 4; ++gq) {
;                 const f32x4 sc = *(const f32x4*)(scp + 32 * eh + 8 * gq + 4 * hi);
;                 u32x2 wv; wv.x = pk2(acc[eh][4 * gq] * sc.x, acc[eh][4 * gq + 1] * sc.y); wv.y = pk2(acc[eh][4 * gq + 2] * sc.z, acc[eh][4 * gq + 3] * sc.w);
;                 *(u32x2*)(yr + 32 * eh + 8 * gq) = wv;
;             }
	v_add_f32_e32 v26, 0, v12
	v_add_f32_e32 v26, v11, v26
	v_cndmask_b32_e64 v28, v10, 0, s[0:1]
	v_add_f32_e32 v26, v28, v26
	v_add_f32_e32 v26, v27, v26
	v_cndmask_b32_e32 v16, 0, v16, vcc
	v_add_f32_e32 v26, v16, v26
	v_add_f32_e32 v26, v9, v26
	v_add_f32_e32 v26, v29, v26
	v_add_f32_e32 v26, v30, v26
	v_cndmask_b32_e64 v14, 0, v14, s[2:3]
	v_add_f32_e32 v26, v14, v26
	v_add_f32_e32 v26, v19, v26
	v_add_f32_e32 v26, v18, v26
	v_add_f32_e32 v26, v21, v26
	v_add_f32_e32 v26, v20, v26
	v_add_f32_e32 v26, v23, v26
	v_add_f32_e32 v26, v22, v26
	v_add_f32_e32 v25, v25, v26
	v_fma_f32 v24, v64, v24, -v11
	v_fma_f32 v25, v64, v25, -v12
	ds_write2st64_b32 v72, v24, v25 offset0:112 offset1:116
	v_add_f32_e32 v24, 0, v13
	v_add_f32_e32 v24, v12, v24
	v_cndmask_b32_e64 v11, v11, 0, s[0:1]
	v_add_f32_e32 v24, v11, v24
	v_add_f32_e32 v24, v28, v24
	v_cndmask_b32_e32 v17, 0, v17, vcc
	v_add_f32_e32 v24, v17, v24
	v_add_f32_e32 v24, v16, v24
	v_add_f32_e32 v24, v9, v24
	v_add_f32_e32 v24, v29, v24
	v_cndmask_b32_e64 v15, 0, v15, s[2:3]
	v_add_f32_e32 v24, v15, v24
	v_add_f32_e32 v24, v14, v24
	v_add_f32_e32 v24, v19, v24
	v_add_f32_e32 v24, v18, v24
	v_add_f32_e32 v24, v21, v24
	v_add_f32_e32 v24, v20, v24
	v_add_f32_e32 v24, v23, v24
	v_add_f32_e32 v22, v22, v24
	v_add_f32_e32 v24, 0, v70
	v_fma_f32 v22, v64, v22, -v13
	v_add_f32_e32 v13, v13, v24
	v_cndmask_b32_e64 v12, v12, 0, s[0:1]
	v_add_f32_e32 v12, v12, v13
	v_add_f32_e32 v11, v11, v12
	v_cndmask_b32_e32 v10, 0, v10, vcc
	v_add_f32_e32 v10, v10, v11
	v_add_f32_e32 v10, v17, v10
	v_add_f32_e32 v10, v16, v10
	v_add_f32_e32 v9, v9, v10
	v_cndmask_b32_e64 v8, 0, v8, s[2:3]
	v_add_f32_e32 v8, v8, v9
	v_add_f32_e32 v8, v15, v8
	v_add_f32_e32 v8, v14, v8
	v_add_f32_e32 v8, v19, v8
	v_add_f32_e32 v8, v18, v8
	v_add_f32_e32 v8, v21, v8
	v_add_f32_e32 v8, v20, v8
	v_add_f32_e32 v8, v23, v8
	v_fma_f32 v8, v64, v8, -v70
	v_and_b32_e32 v70, 0xc0, v68
	ds_write2st64_b32 v72, v22, v8 offset0:120 offset1:124
	v_lshl_add_u32 v8, v67, 10, s19
	v_lshlrev_b32_e32 v64, 2, v70
	v_and_b32_e32 v9, 32, v68
	v_add3_u32 v65, v8, v64, v9
	s_waitcnt lgkmcnt(0)
	s_barrier
	ds_read_b128 v[8:11], v65
	ds_read_b128 v[12:15], v65 offset:16
	ds_read_b128 v[56:59], v65 offset:64
	ds_read_b128 v[60:63], v65 offset:80
	s_not_b32 s2, s18
	v_mov_b32_e32 v68, 0
	s_waitcnt lgkmcnt(3)
	v_cvt_pk_bf16_f32 v8, v8, v9
	v_cvt_pk_bf16_f32 v9, v10, v11
	s_waitcnt lgkmcnt(2)
	v_cvt_pk_bf16_f32 v10, v12, v13
	v_cvt_pk_bf16_f32 v11, v14, v15
	s_waitcnt lgkmcnt(1)
	v_cvt_pk_bf16_f32 v56, v56, v57
	v_cvt_pk_bf16_f32 v57, v58, v59
	v_mfma_f32_32x32x16_bf16 v[16:31], v[0:3], v[8:11], 0
	s_waitcnt lgkmcnt(0)
	v_cvt_pk_bf16_f32 v58, v60, v61
	v_cvt_pk_bf16_f32 v59, v62, v63
	v_mov_b32_e32 v60, 0
	v_mov_b32_e32 v71, 0
	v_mfma_f32_32x32x16_bf16 v[0:15], v[4:7], v[8:11], 0
	v_mfma_f32_32x32x16_bf16 v[16:31], v[32:35], v[56:59], v[16:31]
	v_mfma_f32_32x32x16_bf16 v[0:15], v[44:47], v[56:59], v[0:15]
	ds_read_b128 v[32:35], v65 offset:128
	ds_read_b128 v[44:47], v65 offset:144
	s_waitcnt lgkmcnt(1)
	v_cvt_pk_bf16_f32 v32, v32, v33
	v_cvt_pk_bf16_f32 v33, v34, v35
	s_waitcnt lgkmcnt(0)
	v_cvt_pk_bf16_f32 v34, v44, v45
	v_cvt_pk_bf16_f32 v35, v46, v47
	s_nop 1
	v_mfma_f32_32x32x16_bf16 v[16:31], v[36:39], v[32:35], v[16:31]
	v_mfma_f32_32x32x16_bf16 v[0:15], v[48:51], v[32:35], v[0:15]
	ds_read_b128 v[32:35], v65 offset:192
	ds_read_b128 v[36:39], v65 offset:208
	v_mov_b32_e32 v65, v129
	s_waitcnt lgkmcnt(1)
	v_cvt_pk_bf16_f32 v32, v32, v33
	v_cvt_pk_bf16_f32 v33, v34, v35
	s_waitcnt lgkmcnt(0)
	v_cvt_pk_bf16_f32 v34, v36, v37
	v_cvt_pk_bf16_f32 v35, v38, v39
	v_lshlrev_b32_e32 v36, 1, v70
	v_mov_b32_e32 v37, v129
	v_mfma_f32_32x32x16_bf16 v[16:31], v[40:43], v[32:35], v[16:31]
	v_mov_b32_e32 v70, 0
	v_mfma_f32_32x32x16_bf16 v[0:15], v[52:55], v[32:35], v[0:15]
	v_or_b32_e32 v32, s17, v67
	v_ashrrev_i32_e32 v33, 31, v32
	v_lshlrev_b64 v[32:33], 11, v[32:33]
	v_lshl_add_u64 v[32:33], s[88:89], 0, v[32:33]
	v_lshl_add_u64 v[32:33], v[32:33], 0, v[36:37]
	v_lshlrev_b32_e32 v36, 3, v69
	v_lshl_add_u64 v[34:35], s[12:13], 0, v[64:65]
	v_lshl_add_u64 v[32:33], v[32:33], 0, v[36:37]
	v_lshlrev_b32_e32 v36, 4, v69
	v_lshl_add_u64 v[34:35], v[34:35], 0, v[36:37]
	global_load_dwordx4 v[36:39], v[34:35], off
	v_mov_b32_e32 v64, 0
	v_mov_b32_e32 v65, 0
	v_mov_b32_e32 v67, 0
	v_mov_b32_e32 v69, 0
	s_waitcnt vmcnt(0)
	v_pk_mul_f32 v[16:17], v[16:17], v[36:37]
	v_pk_mul_f32 v[18:19], v[18:19], v[38:39]
	v_cvt_pk_bf16_f32 v16, v16, v17
	v_cvt_pk_bf16_f32 v17, v18, v19
	global_store_dwordx2 v[32:33], v[16:17], off offset:512
	global_load_dwordx4 v[16:19], v[34:35], off offset:32
	s_waitcnt vmcnt(0)
	v_pk_mul_f32 v[16:17], v[20:21], v[16:17]
	v_pk_mul_f32 v[18:19], v[22:23], v[18:19]
	v_cvt_pk_bf16_f32 v16, v16, v17
	v_cvt_pk_bf16_f32 v17, v18, v19
	global_store_dwordx2 v[32:33], v[16:17], off offset:528
	global_load_dwordx4 v[16:19], v[34:35], off offset:64
	s_waitcnt vmcnt(0)
	v_pk_mul_f32 v[16:17], v[24:25], v[16:17]
	v_pk_mul_f32 v[18:19], v[26:27], v[18:19]
	v_cvt_pk_bf16_f32 v16, v16, v17
	v_cvt_pk_bf16_f32 v17, v18, v19
	global_store_dwordx2 v[32:33], v[16:17], off offset:544
	global_load_dwordx4 v[16:19], v[34:35], off offset:96
	s_waitcnt vmcnt(0)
	v_pk_mul_f32 v[16:17], v[28:29], v[16:17]
	v_pk_mul_f32 v[18:19], v[30:31], v[18:19]
	v_cvt_pk_bf16_f32 v16, v16, v17
	v_cvt_pk_bf16_f32 v17, v18, v19
	global_store_dwordx2 v[32:33], v[16:17], off offset:560
	global_load_dwordx4 v[16:19], v[34:35], off offset:128
	s_waitcnt vmcnt(0)
	v_pk_mul_f32 v[0:1], v[0:1], v[16:17]
	v_pk_mul_f32 v[2:3], v[2:3], v[18:19]
	v_cvt_pk_bf16_f32 v0, v0, v1
	v_cvt_pk_bf16_f32 v1, v2, v3
	global_store_dwordx2 v[32:33], v[0:1], off offset:576
	global_load_dwordx4 v[0:3], v[34:35], off offset:160
	s_waitcnt vmcnt(0)
	v_pk_mul_f32 v[0:1], v[4:5], v[0:1]
	v_pk_mul_f32 v[2:3], v[6:7], v[2:3]
	v_cvt_pk_bf16_f32 v0, v0, v1
	v_cvt_pk_bf16_f32 v1, v2, v3
	global_store_dwordx2 v[32:33], v[0:1], off offset:592
	global_load_dwordx4 v[0:3], v[34:35], off offset:192
	s_waitcnt vmcnt(0)
	v_pk_mul_f32 v[0:1], v[8:9], v[0:1]
	v_pk_mul_f32 v[2:3], v[10:11], v[2:3]
	v_cvt_pk_bf16_f32 v0, v0, v1
	v_cvt_pk_bf16_f32 v1, v2, v3
	global_store_dwordx2 v[32:33], v[0:1], off offset:608
	global_load_dwordx4 v[0:3], v[34:35], off offset:224
	s_waitcnt vmcnt(0)
	v_pk_mul_f32 v[0:1], v[12:13], v[0:1]
	v_pk_mul_f32 v[2:3], v[14:15], v[2:3]
	v_cvt_pk_bf16_f32 v0, v0, v1
	v_cvt_pk_bf16_f32 v1, v2, v3
	global_store_dwordx2 v[32:33], v[0:1], off offset:624
	v_lshlrev_b32_e32 v0, 2, v66
	v_add_u32_e32 v1, -2, v0
	v_cmp_lt_i32_e32 vcc, s2, v1
	v_add_u32_e32 v96, s17, v1
	v_mov_b32_e32 v66, 0
	s_barrier
	s_and_saveexec_b64 s[0:1], vcc
	s_cbranch_execz .LBB0_180
	v_mad_i64_i32 v[2:3], s[18:19], v96, s70, v[88:89]
	global_load_dwordx4 v[64:67], v[2:3], off offset:1536
	global_load_dwordx4 v[68:71], v[2:3], off offset:2560
